# speedup vs baseline: 1.0818x; 1.0003x over previous
; DEV float bf2f(u16 h) { return __uint_as_float(((unsigned)h) << 16); }
; PHASE void lru_phase(const Params& p, int layer, const u16* __restrict__ GC, u16* __restrict__ OC, float* __restrict__ LA, ...
;     ...
;     if (tid < 128) {
;       const int ch = ch0 + tid;
;       const size_t cidx = ((size_t)b * 256 + c) * 2048 + ch;
;       float h = pass3 ? LC[cidx] : 0.f;
;       float Ap = 1.f;
; #pragma unroll 8
;       for (int t = 0; t < 64; ++t) {
;         const float e = bf2f(sR[t * 128 + tid]);
;         const float bb = bf2f(sG[t * 128 + tid]);
;         h = (h - e * h) + bb;
;         Ap = Ap - e * Ap;
;         if (pass3) sR[t * 128 + tid] = f2bf(h);
;       }
;       if (!pass3) { LA[cidx] = Ap; LH[cidx] = h; }
;     }
.LBB0_376:
	v_add_u32_e32 v3, s22, v132
	ds_read_u16 v208, v3
	ds_read_u16 v209, v3 offset:16384
	ds_read_u16 v210, v3 offset:256
	ds_read_u16 v211, v3 offset:16640
	ds_read_u16 v212, v3 offset:512
	ds_read_u16 v213, v3 offset:16896
	ds_read_u16 v214, v3 offset:768
	ds_read_u16 v215, v3 offset:17152
	ds_read_u16 v216, v3 offset:1024
	ds_read_u16 v217, v3 offset:17408
	ds_read_u16 v218, v3 offset:1280
	ds_read_u16 v219, v3 offset:17664
	ds_read_u16 v220, v3 offset:1536
	ds_read_u16 v221, v3 offset:17920
	ds_read_u16 v222, v3 offset:1792
	ds_read_u16 v223, v3 offset:18176
	s_waitcnt lgkmcnt(0)
	v_mov_b32_e32 v4, v208
	v_mov_b32_e32 v5, v209
	v_cndmask_b32_e64 v6, 0, 1, s[2:3]
	v_cmp_ne_u32_e64 s[0:1], 1, v6
	s_andn2_b64 vcc, exec, s[2:3]
	s_waitcnt lgkmcnt(1)
	v_lshlrev_b32_e32 v4, 16, v4
	s_waitcnt lgkmcnt(0)
	v_lshlrev_b32_e32 v5, 16, v5
	s_waitcnt vmcnt(0)
	v_fma_f32 v6, -v8, v4, v8
	v_add_f32_e32 v6, v6, v5
	s_cbranch_vccnz .LBB0_378
	v_bfe_u32 v5, v6, 16, 1
	v_add3_u32 v5, v6, v5, s71
	ds_write_b16_d16_hi v3, v5
.LBB0_378:
	v_mov_b32_e32 v5, v210
	v_mov_b32_e32 v7, v211
	s_and_b64 vcc, exec, s[0:1]
	s_waitcnt lgkmcnt(1)
	v_lshlrev_b32_e32 v5, 16, v5
	s_waitcnt lgkmcnt(0)
	v_lshlrev_b32_e32 v7, 16, v7
	v_fma_f32 v6, -v6, v5, v6
	v_add_f32_e32 v7, v6, v7
	s_cbranch_vccnz .LBB0_380
	v_bfe_u32 v6, v7, 16, 1
	v_add3_u32 v6, v7, v6, s71
	ds_write_b16_d16_hi v3, v6 offset:256
.LBB0_380:
	v_mov_b32_e32 v6, v212
	v_mov_b32_e32 v8, v213
	s_and_b64 vcc, exec, s[0:1]
	s_waitcnt lgkmcnt(1)
	v_lshlrev_b32_e32 v6, 16, v6
	s_waitcnt lgkmcnt(0)
	v_lshlrev_b32_e32 v8, 16, v8
	v_fma_f32 v7, -v7, v6, v7
	v_add_f32_e32 v8, v7, v8
	s_cbranch_vccnz .LBB0_382
	v_bfe_u32 v7, v8, 16, 1
	v_add3_u32 v7, v8, v7, s71
	ds_write_b16_d16_hi v3, v7 offset:512
.LBB0_382:
	v_mov_b32_e32 v7, v214
	v_mov_b32_e32 v9, v215
	s_and_b64 vcc, exec, s[0:1]
	s_waitcnt lgkmcnt(1)
	v_lshlrev_b32_e32 v7, 16, v7
	s_waitcnt lgkmcnt(0)
	v_lshlrev_b32_e32 v9, 16, v9
	v_fma_f32 v8, -v8, v7, v8
	v_add_f32_e32 v8, v8, v9
	s_cbranch_vccnz .LBB0_384
	v_bfe_u32 v9, v8, 16, 1
	v_add3_u32 v9, v8, v9, s71
	ds_write_b16_d16_hi v3, v9 offset:768
.LBB0_384:
	v_mov_b32_e32 v9, v216
	v_mov_b32_e32 v10, v217
	s_and_b64 vcc, exec, s[0:1]
	s_waitcnt lgkmcnt(1)
	v_lshlrev_b32_e32 v9, 16, v9
	s_waitcnt lgkmcnt(0)
	v_lshlrev_b32_e32 v10, 16, v10
	v_fma_f32 v8, -v8, v9, v8
	v_add_f32_e32 v8, v8, v10
	s_cbranch_vccnz .LBB0_386
	v_bfe_u32 v10, v8, 16, 1
	v_add3_u32 v10, v8, v10, s71
	ds_write_b16_d16_hi v3, v10 offset:1024
.LBB0_386:
	v_mov_b32_e32 v10, v218
	v_mov_b32_e32 v11, v219
	s_and_b64 vcc, exec, s[0:1]
	s_waitcnt lgkmcnt(1)
	v_lshlrev_b32_e32 v10, 16, v10
	s_waitcnt lgkmcnt(0)
	v_lshlrev_b32_e32 v11, 16, v11
	v_fma_f32 v8, -v8, v10, v8
	v_add_f32_e32 v8, v8, v11
	s_cbranch_vccnz .LBB0_388
	v_bfe_u32 v11, v8, 16, 1
	v_add3_u32 v11, v8, v11, s71
	ds_write_b16_d16_hi v3, v11 offset:1280
.LBB0_388:
	v_mov_b32_e32 v11, v220
	v_mov_b32_e32 v12, v221
	s_and_b64 vcc, exec, s[0:1]
	s_waitcnt lgkmcnt(1)
	v_lshlrev_b32_e32 v11, 16, v11
	s_waitcnt lgkmcnt(0)
	v_lshlrev_b32_e32 v12, 16, v12
	v_fma_f32 v8, -v8, v11, v8
	v_add_f32_e32 v8, v8, v12
	s_cbranch_vccnz .LBB0_390
	v_bfe_u32 v12, v8, 16, 1
	v_add3_u32 v12, v8, v12, s71
	ds_write_b16_d16_hi v3, v12 offset:1536
.LBB0_390:
	v_mov_b32_e32 v12, v222
	v_mov_b32_e32 v13, v223
	s_and_b64 vcc, exec, s[0:1]
	s_waitcnt lgkmcnt(1)
	v_lshlrev_b32_e32 v12, 16, v12
	s_waitcnt lgkmcnt(0)
	v_lshlrev_b32_e32 v13, 16, v13
	v_fma_f32 v8, -v8, v12, v8
	v_add_f32_e32 v8, v8, v13
	s_cbranch_vccnz .LBB0_375
	v_bfe_u32 v13, v8, 16, 1
	v_add3_u32 v13, v8, v13, s71
	ds_write_b16_d16_hi v3, v13 offset:1792
	s_branch .LBB0_375
